# grid barrier: wave 1 issues and waits for the L1 invalidate at seam entry so thread 0's arrival/poll/release path never waits behind it
# speedup vs baseline: 1.0399x; 1.0003x over previous
; __device__ __forceinline__ void xcd_barrier(const XcdBarrier& b) {
;     asm volatile("s_waitcnt vmcnt(0)" ::: "memory");
;     __syncthreads();
;     if (threadIdx.x == 0) {
;         unsigned* bar = b.bar;
;         __builtin_amdgcn_s_waitcnt(0);
;         unsigned nloc = b.st[0], nx = b.st[1];
;         if (nloc == 0u) { xcd_barrier_complete(bar, b.x, nloc, nx); b.st[0] = nloc; b.st[1] = nx; }
.LBB0_76:
	s_cmp_gt_i32 s95, 1
	s_cselect_b64 s[4:5], -1, 0
	s_and_b64 s[6:7], s[6:7], s[4:5]
	s_andn2_b64 vcc, exec, s[6:7]
	s_cbranch_vccnz .LBB0_130
	s_waitcnt vmcnt(0)
	s_waitcnt lgkmcnt(0)
	s_barrier
	v_readfirstlane_b32 s98, v206
	s_nop 3
	s_lshr_b32 s98, s98, 6
	s_cmp_lg_u32 s98, 1
	s_cbranch_scc1 .Lw1_0
	buffer_inv sc1
	s_waitcnt vmcnt(0)
.Lw1_0:
	s_and_saveexec_b64 s[6:7], s[88:89]
	s_cbranch_execz .LBB0_129
	s_add_i32 s8, 0, 0x25fc0
	v_mov_b32_e32 v0, s8
	s_waitcnt vmcnt(0) expcnt(0) lgkmcnt(0)
	ds_read_b32 v2, v0
	s_add_i32 s8, 0, 0x25fc4
	v_mov_b32_e32 v0, s8
	ds_read_b32 v0, v0
	s_waitcnt lgkmcnt(1)
	v_cmp_ne_u32_e32 vcc, 0, v2
	s_cbranch_vccnz .LBB0_93
	s_load_dwordx2 s[12:13], s[68:69], 0x4
	s_add_u32 s8, s92, 0x80200
	s_addc_u32 s9, s93, 0
	s_add_u32 s10, s92, 0x80400
	s_addc_u32 s11, s93, 0
	s_waitcnt lgkmcnt(0)
	s_mul_i32 s33, s12, s3
	s_add_u32 s12, s92, 0x80500
	s_mul_i32 s33, s33, s13
	s_addc_u32 s13, s93, 0
	s_add_u32 s14, s92, 0x80600
	s_addc_u32 s15, s93, 0
	s_add_u32 s16, s92, 0x80700
	s_addc_u32 s17, s93, 0
	s_add_u32 s18, s92, 0x80800
	s_addc_u32 s19, s93, 0
	s_add_u32 s20, s92, 0x80900
	s_addc_u32 s21, s93, 0
	s_add_u32 s22, s92, 0x80a00
	s_addc_u32 s23, s93, 0
	s_add_u32 s24, s92, 0x80b00
	s_addc_u32 s25, s93, 0
	s_add_u32 s26, s92, 0x80c00
	s_addc_u32 s27, s93, 0
	s_add_u32 s28, s92, 0x80d00
	s_addc_u32 s29, s93, 0
	s_add_u32 s30, s92, 0x80e00
	s_addc_u32 s31, s93, 0
	s_add_u32 s34, s92, 0x80f00
	s_addc_u32 s35, s93, 0
	s_add_u32 s36, s92, 0x81000
	s_addc_u32 s37, s93, 0
	s_add_u32 s38, s92, 0x81100
	s_addc_u32 s39, s93, 0
	s_add_u32 s40, s92, 0x81200
	s_addc_u32 s41, s93, 0
	s_add_u32 s42, s92, 0x81300
	s_addc_u32 s43, s93, 0
	s_mov_b32 s50, 1
	v_mov_b32_e32 v16, 0
	s_branch .LBB0_81

; __device__ __forceinline__ unsigned xb_ld(unsigned* p)              { return __hip_atomic_load(p, __ATOMIC_RELAXED, __HIP_MEMORY_SCOPE_AGENT); }
; __device__ __forceinline__ unsigned xb_add(unsigned* p, unsigned v) { return __hip_atomic_fetch_add(p, v, __ATOMIC_RELAXED, __HIP_MEMORY_SCOPE_AGENT); }
; #define XB_SPIN(cond, bar) do { unsigned _sp = 0; while (cond) { __builtin_amdgcn_s_sleep(1); \
;     if ((++_sp & 255u) == 0u) { if (xb_ld(&(bar)[XB_TMO])) break; if (_sp > XB_SPIN_CAP) { atomicAdd(&(bar)[XB_TMO], 1u); break; } } } } while (0)
; __device__ __forceinline__ void xcd_barrier(const XcdBarrier& b) {
;     ...
;         const unsigned old = xb_add(&bar[XB_XSUB(b.x)], 1u);
;         const unsigned gen = old / nloc;
;         if (old + 1u == (gen + 1u) * nloc) {
;             __builtin_amdgcn_fence(__ATOMIC_RELEASE, "agent");
;             asm volatile("s_waitcnt vmcnt(0)" ::: "memory");
;             const unsigned og = xb_add(&bar[XB_TOP], 1u);
;             const unsigned tg = og / nx;
;             if (og + 1u == (tg + 1u) * nx) xb_add(&bar[XB_TOPGEN], 1u);
;             else XB_SPIN(xb_ld(&bar[XB_TOPGEN]) == tg, bar);
;             __builtin_amdgcn_fence(__ATOMIC_ACQUIRE, "agent");
;             xb_add(&bar[XB_XGEN(b.x)], 1u);
;             asm volatile("s_waitcnt vmcnt(0)" ::: "memory");
;         } else {
;             XB_SPIN(xb_ld(&bar[XB_XGEN(b.x)]) == gen, bar);
;             __builtin_amdgcn_fence(__ATOMIC_ACQUIRE, "agent");
;             asm volatile("s_waitcnt vmcnt(0)" ::: "memory");
.LBB0_95:
	s_or_b64 exec, exec, s[12:13]
	v_cvt_f32_u32_e32 v4, v2
	s_waitcnt vmcnt(0)
	v_readfirstlane_b32 s10, v3
	v_sub_u32_e32 v3, 0, v2
	v_rcp_iflag_f32_e32 v4, v4
	v_add_u32_e32 v5, s10, v1
	v_mul_f32_e32 v4, 0x4f7ffffe, v4
	v_cvt_u32_f32_e32 v4, v4
	v_mul_lo_u32 v1, v3, v4
	v_mul_hi_u32 v1, v4, v1
	v_add_u32_e32 v1, v4, v1
	v_mul_hi_u32 v1, v5, v1
	v_mul_lo_u32 v3, v1, v2
	v_sub_u32_e32 v3, v5, v3
	v_add_u32_e32 v4, 1, v1
	v_cmp_ge_u32_e32 vcc, v3, v2
	s_nop 1
	v_cndmask_b32_e32 v1, v1, v4, vcc
	v_sub_u32_e32 v4, v3, v2
	v_cndmask_b32_e32 v3, v3, v4, vcc
	v_add_u32_e32 v4, 1, v1
	v_cmp_ge_u32_e32 vcc, v3, v2
	v_add_u32_e32 v3, 1, v5
	s_nop 0
	v_cndmask_b32_e32 v1, v1, v4, vcc
	v_mul_lo_u32 v4, v2, v1
	v_add_u32_e32 v2, v4, v2
	v_cmp_ne_u32_e32 vcc, v3, v2
	s_and_saveexec_b64 s[10:11], vcc
	s_xor_b64 s[10:11], exec, s[10:11]
	s_cbranch_execz .LBB0_109
	s_nop 0
	s_waitcnt lgkmcnt(0)
	v_mov_b32_e32 v0, 0x2000
	global_load_dword v0, v0, s[8:9] offset:1024 sc1
	s_add_u32 s16, s8, 0x2400
	s_addc_u32 s17, s9, 0
	s_waitcnt vmcnt(0)
	v_cmp_eq_u32_e32 vcc, v0, v1
	s_and_saveexec_b64 s[12:13], vcc
	s_cbranch_execz .LBB0_108
	s_add_u32 s14, s92, 0x80200
	s_addc_u32 s15, s93, 0
	s_mov_b32 s28, 1
	s_mov_b64 s[18:19], 0
	v_mov_b32_e32 v0, 0
	s_branch .LBB0_99

; __device__ __forceinline__ unsigned xb_add(unsigned* p, unsigned v) { return __hip_atomic_fetch_add(p, v, __ATOMIC_RELAXED, __HIP_MEMORY_SCOPE_AGENT); }
; __device__ __forceinline__ void xcd_barrier(const XcdBarrier& b) {
;     ...
;         if (old + 1u == (gen + 1u) * nloc) {
;             __builtin_amdgcn_fence(__ATOMIC_RELEASE, "agent");
;             asm volatile("s_waitcnt vmcnt(0)" ::: "memory");
;             const unsigned og = xb_add(&bar[XB_TOP], 1u);
;             const unsigned tg = og / nx;
.LBB0_109:
	s_andn2_saveexec_b64 s[10:11], s[10:11]
	s_cbranch_execz .LBB0_129
	s_mov_b64 s[10:11], exec
	buffer_wbl2 sc1
	s_waitcnt lgkmcnt(0)
	s_waitcnt vmcnt(0)
	s_nop 0
	v_mbcnt_lo_u32_b32 v1, s10, 0
	v_mbcnt_hi_u32_b32 v1, s11, v1
	v_cmp_eq_u32_e32 vcc, 0, v1
	s_and_saveexec_b64 s[12:13], vcc
	s_cbranch_execz .LBB0_112
	s_bcnt1_i32_b64 s10, s[10:11]
	v_mov_b32_e32 v2, 0x83000
	v_mov_b32_e32 v3, s10
	global_atomic_add v2, v2, v3, s[92:93] offset:1024 sc0

; __device__ __forceinline__ void xcd_barrier(const XcdBarrier& b) {
;     asm volatile("s_waitcnt vmcnt(0)" ::: "memory");
;     __syncthreads();
;     if (threadIdx.x == 0) {
.LBB0_237:
	s_cmp_gt_i32 s95, 2
	s_cselect_b64 s[4:5], -1, 0
	s_and_b64 s[6:7], s[8:9], s[4:5]
	s_andn2_b64 vcc, exec, s[6:7]
	s_cbranch_vccnz .LBB0_291
	s_waitcnt vmcnt(0)
	s_waitcnt lgkmcnt(0)
	s_barrier
	v_readfirstlane_b32 s98, v206
	s_nop 3
	s_lshr_b32 s98, s98, 6
	s_cmp_lg_u32 s98, 1
	s_cbranch_scc1 .Lw1_1
	buffer_inv sc1
	s_waitcnt vmcnt(0)

; __device__ __forceinline__ void xcd_barrier(const XcdBarrier& b) {
;     asm volatile("s_waitcnt vmcnt(0)" ::: "memory");
;     __syncthreads();
;     if (threadIdx.x == 0) {
.LBB0_338:
	s_cmp_gt_i32 s95, 3
	s_cselect_b64 s[4:5], -1, 0
	s_and_b64 s[6:7], s[10:11], s[4:5]
	s_andn2_b64 vcc, exec, s[6:7]
	s_cbranch_vccnz .LBB0_392
	s_waitcnt vmcnt(0)
	s_waitcnt lgkmcnt(0)
	s_barrier
	v_readfirstlane_b32 s98, v206
	s_nop 3
	s_lshr_b32 s98, s98, 6
	s_cmp_lg_u32 s98, 1
	s_cbranch_scc1 .Lw1_2
	buffer_inv sc1
	s_waitcnt vmcnt(0)

; __device__ __forceinline__ unsigned xb_add(unsigned* p, unsigned v) { return __hip_atomic_fetch_add(p, v, __ATOMIC_RELAXED, __HIP_MEMORY_SCOPE_AGENT); }
; __device__ __forceinline__ void xcd_barrier(const XcdBarrier& b) {
;     ...
;         const unsigned old = xb_add(&bar[XB_XSUB(b.x)], 1u);
;         const unsigned gen = old / nloc;
;         if (old + 1u == (gen + 1u) * nloc) {
;             __builtin_amdgcn_fence(__ATOMIC_RELEASE, "agent");
;             asm volatile("s_waitcnt vmcnt(0)" ::: "memory");
;             const unsigned og = xb_add(&bar[XB_TOP], 1u);
;             const unsigned tg = og / nx;
;             if (og + 1u == (tg + 1u) * nx) xb_add(&bar[XB_TOPGEN], 1u);
.LBB0_371:
	s_andn2_saveexec_b64 s[10:11], s[10:11]
	s_cbranch_execz .LBB0_391
	s_mov_b64 s[10:11], exec
	s_cmp_eq_u32 s99, 1
	s_cbranch_scc1 .Lloc_2
	buffer_wbl2 sc1
	s_waitcnt lgkmcnt(0)
	s_waitcnt vmcnt(0)
	s_nop 0
	v_mbcnt_lo_u32_b32 v1, s10, 0
	v_mbcnt_hi_u32_b32 v1, s11, v1
	v_cmp_eq_u32_e32 vcc, 0, v1
	s_and_saveexec_b64 s[12:13], vcc
	s_cbranch_execz .LBB0_374
	s_bcnt1_i32_b64 s10, s[10:11]
	v_mov_b32_e32 v2, 0x83000
	v_mov_b32_e32 v3, s10
	global_atomic_add v2, v2, v3, s[92:93] offset:1024 sc0

; __device__ __forceinline__ unsigned xb_add(unsigned* p, unsigned v) { return __hip_atomic_fetch_add(p, v, __ATOMIC_RELAXED, __HIP_MEMORY_SCOPE_AGENT); }
; __device__ __forceinline__ void xcd_barrier(const XcdBarrier& b) {
;     ...
;             __builtin_amdgcn_fence(__ATOMIC_ACQUIRE, "agent");
;             xb_add(&bar[XB_XGEN(b.x)], 1u);
;             asm volatile("s_waitcnt vmcnt(0)" ::: "memory");
.Lloc_2:
	s_nop 0
	v_mov_b32_e32 v0, 0x2000
	v_mov_b32_e32 v1, 1
	global_atomic_add v0, v1, s[8:9] offset:1024
	s_nop 0

; __device__ __forceinline__ void xcd_barrier(const XcdBarrier& b) {
;     asm volatile("s_waitcnt vmcnt(0)" ::: "memory");
;     __syncthreads();
;     if (threadIdx.x == 0) {
.LBB0_672:
	s_cmp_gt_i32 s95, 4
	s_cselect_b64 s[4:5], -1, 0
	s_and_b64 s[6:7], s[12:13], s[4:5]
	s_andn2_b64 vcc, exec, s[6:7]
	s_cbranch_vccnz .LBB0_726
	s_waitcnt vmcnt(0)
	s_waitcnt lgkmcnt(0)
	s_barrier
	v_readfirstlane_b32 s98, v206
	s_nop 3
	s_lshr_b32 s98, s98, 6
	s_cmp_lg_u32 s98, 1
	s_cbranch_scc1 .Lw1_3
	buffer_inv sc1
	s_waitcnt vmcnt(0)

; __device__ __forceinline__ void xcd_barrier(const XcdBarrier& b) {
;     asm volatile("s_waitcnt vmcnt(0)" ::: "memory");
;     __syncthreads();
;     if (threadIdx.x == 0) {
.LBB0_893:
	s_cmp_gt_i32 s95, 5
	s_cselect_b64 s[4:5], -1, 0
	s_and_b64 s[6:7], s[10:11], s[4:5]
	s_andn2_b64 vcc, exec, s[6:7]
	s_cbranch_vccnz .LBB0_947
	s_waitcnt vmcnt(0)
	s_waitcnt lgkmcnt(0)
	s_barrier
	v_readfirstlane_b32 s98, v206
	s_nop 3
	s_lshr_b32 s98, s98, 6
	s_cmp_lg_u32 s98, 1
	s_cbranch_scc1 .Lw1_4
	buffer_inv sc1
	s_waitcnt vmcnt(0)

; __device__ __forceinline__ void xcd_barrier(const XcdBarrier& b) {
;     asm volatile("s_waitcnt vmcnt(0)" ::: "memory");
;     __syncthreads();
;     if (threadIdx.x == 0) {
;         unsigned* bar = b.bar;
;         __builtin_amdgcn_s_waitcnt(0);
;         unsigned nloc = b.st[0], nx = b.st[1];
;         if (nloc == 0u) { xcd_barrier_complete(bar, b.x, nloc, nx); b.st[0] = nloc; b.st[1] = nx; }
.LBB0_1069:
	s_cmp_gt_i32 s95, 6
	s_cselect_b64 s[4:5], -1, 0
	s_and_b64 s[6:7], s[16:17], s[4:5]
	s_andn2_b64 vcc, exec, s[6:7]
	s_cbranch_vccnz .LBB0_1123
	s_waitcnt vmcnt(0)
	s_waitcnt lgkmcnt(0)
	s_barrier
	v_readfirstlane_b32 s98, v206
	s_nop 3
	s_lshr_b32 s98, s98, 6
	s_cmp_lg_u32 s98, 1
	s_cbranch_scc1 .Lw1_5
	buffer_inv sc1
	s_waitcnt vmcnt(0)
.Lw1_5:
	s_and_saveexec_b64 s[6:7], s[88:89]
	s_cbranch_execz .LBB0_1122
	s_add_i32 s8, 0, 0x25fc0
	s_waitcnt vmcnt(23)
	v_mov_b32_e32 v0, s8
	s_waitcnt vmcnt(0) expcnt(0) lgkmcnt(0)
	ds_read_b32 v2, v0
	s_add_i32 s8, 0, 0x25fc4
	v_mov_b32_e32 v0, s8
	ds_read_b32 v0, v0
	s_waitcnt lgkmcnt(1)
	v_cmp_ne_u32_e32 vcc, 0, v2
	s_cbranch_vccnz .LBB0_1086
	s_load_dwordx2 s[12:13], s[68:69], 0x4
	s_add_u32 s8, s92, 0x80200
	s_addc_u32 s9, s93, 0
	s_add_u32 s10, s92, 0x80400
	s_addc_u32 s11, s93, 0
	s_waitcnt lgkmcnt(0)
	s_mul_i32 s33, s12, s3
	s_add_u32 s12, s92, 0x80500
	s_mul_i32 s33, s33, s13
	s_addc_u32 s13, s93, 0
	s_add_u32 s14, s92, 0x80600
	s_addc_u32 s15, s93, 0
	s_add_u32 s16, s92, 0x80700
	s_addc_u32 s17, s93, 0
	s_add_u32 s18, s92, 0x80800
	s_addc_u32 s19, s93, 0
	s_add_u32 s20, s92, 0x80900
	s_addc_u32 s21, s93, 0
	s_add_u32 s22, s92, 0x80a00
	s_addc_u32 s23, s93, 0
	s_add_u32 s24, s92, 0x80b00
	s_addc_u32 s25, s93, 0
	s_add_u32 s26, s92, 0x80c00
	s_addc_u32 s27, s93, 0
	s_add_u32 s28, s92, 0x80d00
	s_addc_u32 s29, s93, 0
	s_add_u32 s30, s92, 0x80e00
	s_addc_u32 s31, s93, 0
	s_add_u32 s34, s92, 0x80f00
	s_addc_u32 s35, s93, 0
	s_add_u32 s36, s92, 0x81000
	s_addc_u32 s37, s93, 0
	s_add_u32 s38, s92, 0x81100
	s_addc_u32 s39, s93, 0
	s_add_u32 s40, s92, 0x81200
	s_addc_u32 s41, s93, 0
	s_add_u32 s42, s92, 0x81300
	s_addc_u32 s43, s93, 0
	s_mov_b32 s50, 1
	v_mov_b32_e32 v16, 0
	s_branch .LBB0_1074

; __device__ __forceinline__ void xcd_barrier(const XcdBarrier& b) {
;     asm volatile("s_waitcnt vmcnt(0)" ::: "memory");
;     __syncthreads();
;     if (threadIdx.x == 0) {
;         unsigned* bar = b.bar;
;         __builtin_amdgcn_s_waitcnt(0);
;         unsigned nloc = b.st[0], nx = b.st[1];
;         if (nloc == 0u) { xcd_barrier_complete(bar, b.x, nloc, nx); b.st[0] = nloc; b.st[1] = nx; }
.LBB0_1148:
	s_cmp_gt_i32 s95, 7
	s_cselect_b64 s[6:7], -1, 0
	s_and_b64 s[4:5], s[4:5], s[6:7]
	s_andn2_b64 vcc, exec, s[4:5]
	s_cbranch_vccnz .LBB0_1203
	s_waitcnt vmcnt(0)
	s_waitcnt lgkmcnt(0)
	s_barrier
	v_readfirstlane_b32 s98, v206
	s_nop 3
	s_lshr_b32 s98, s98, 6
	s_cmp_lg_u32 s98, 1
	s_cbranch_scc1 .Lw1_6
	buffer_inv sc1
	s_waitcnt vmcnt(0)
.Lw1_6:
	s_and_saveexec_b64 s[4:5], s[88:89]
	s_cbranch_execz .LBB0_1202
	s_add_i32 s8, 0, 0x25fc0
	s_waitcnt vmcnt(23)
	v_mov_b32_e32 v0, s8
	s_waitcnt vmcnt(0) expcnt(0) lgkmcnt(0)
	ds_read_b32 v2, v0
	s_add_i32 s8, 0, 0x25fc4
	v_mov_b32_e32 v0, s8
	ds_read_b32 v0, v0
	s_waitcnt lgkmcnt(1)
	v_cmp_ne_u32_e32 vcc, 0, v2
	s_cbranch_vccnz .LBB0_1166
	s_load_dwordx2 s[12:13], s[68:69], 0x4
	s_add_u32 s8, s92, 0x80200
	s_addc_u32 s9, s93, 0
	s_add_u32 s10, s92, 0x80400
	s_addc_u32 s11, s93, 0
	s_waitcnt lgkmcnt(0)
	s_mul_i32 s33, s12, s3
	s_add_u32 s12, s92, 0x80500
	s_mul_i32 s33, s33, s13
	s_addc_u32 s13, s93, 0
	s_add_u32 s14, s92, 0x80600
	s_addc_u32 s15, s93, 0
	s_add_u32 s16, s92, 0x80700
	s_addc_u32 s17, s93, 0
	s_add_u32 s18, s92, 0x80800
	s_addc_u32 s19, s93, 0
	s_add_u32 s20, s92, 0x80900
	s_addc_u32 s21, s93, 0
	s_add_u32 s22, s92, 0x80a00
	s_addc_u32 s23, s93, 0
	s_add_u32 s24, s92, 0x80b00
	s_addc_u32 s25, s93, 0
	s_add_u32 s26, s92, 0x80c00
	s_addc_u32 s27, s93, 0
	s_add_u32 s28, s92, 0x80d00
	s_addc_u32 s29, s93, 0
	s_add_u32 s30, s92, 0x80e00
	s_addc_u32 s31, s93, 0
	s_add_u32 s34, s92, 0x80f00
	s_addc_u32 s35, s93, 0
	s_add_u32 s36, s92, 0x81000
	s_addc_u32 s37, s93, 0
	s_add_u32 s38, s92, 0x81100
	s_addc_u32 s39, s93, 0
	s_add_u32 s40, s92, 0x81200
	s_addc_u32 s41, s93, 0
	s_add_u32 s42, s92, 0x81300
	s_addc_u32 s43, s93, 0
	s_mov_b32 s50, 1
	v_mov_b32_e32 v16, 0
	s_branch .LBB0_1153

; __device__ __forceinline__ void xcd_barrier(const XcdBarrier& b) {
;     asm volatile("s_waitcnt vmcnt(0)" ::: "memory");
;     __syncthreads();
;     if (threadIdx.x == 0) {
.LBB0_1246:
	s_cmp_gt_i32 s95, 8
	s_cselect_b64 s[4:5], -1, 0
	s_and_b64 s[6:7], s[8:9], s[4:5]
	s_andn2_b64 vcc, exec, s[6:7]
	s_cbranch_vccnz .LBB0_1300
	s_waitcnt vmcnt(0)
	s_waitcnt lgkmcnt(0)
	s_barrier
	v_readfirstlane_b32 s98, v206
	s_nop 3
	s_lshr_b32 s98, s98, 6
	s_cmp_lg_u32 s98, 1
	s_cbranch_scc1 .Lw1_7
	buffer_inv sc1
	s_waitcnt vmcnt(0)

; __device__ __forceinline__ void xcd_barrier(const XcdBarrier& b) {
;     asm volatile("s_waitcnt vmcnt(0)" ::: "memory");
;     __syncthreads();
;     if (threadIdx.x == 0) {
.LBB0_1317:
	s_cmp_gt_i32 s95, 9
	s_cselect_b64 s[4:5], -1, 0
	s_and_b64 s[6:7], s[8:9], s[4:5]
	s_andn2_b64 vcc, exec, s[6:7]
	s_cbranch_vccnz .LBB0_1371
	s_waitcnt vmcnt(0)
	s_waitcnt lgkmcnt(0)
	s_barrier
	v_readfirstlane_b32 s98, v206
	s_nop 3
	s_lshr_b32 s98, s98, 6
	s_cmp_lg_u32 s98, 1
	s_cbranch_scc1 .Lw1_8
	buffer_inv sc1
	s_waitcnt vmcnt(0)
